# baseline (speedup 1.0000x reference)
.LBB0_714:
	s_or_b64 exec, exec, s[10:11]
	s_barrier
	s_and_saveexec_b64 s[10:11], s[8:9]
	s_cbranch_execz .LBB0_703
	v_lshlrev_b32_e32 v4, 9, v14
	v_and_or_b32 v4, v4, s49, v15
	v_add_u32_e32 v4, s6, v4
	v_readlane_b32 s8, v240, 17
	v_ashrrev_i32_e32 v5, 31, v4
	v_readlane_b32 s9, v240, 18
	s_nop 1
	v_lshl_add_u64 v[6:7], v[4:5], 2, s[8:9]
	v_add_u32_e32 v22, 0x800, v4
	v_ashrrev_i32_e32 v23, 31, v22
	v_lshl_add_u64 v[22:23], v[22:23], 2, s[8:9]
	v_add_u32_e32 v24, 0x1000, v4
	v_ashrrev_i32_e32 v25, 31, v24
	v_lshl_add_u64 v[24:25], v[24:25], 2, s[8:9]
	v_add_u32_e32 v26, 0x1800, v4
	v_ashrrev_i32_e32 v27, 31, v26
	v_lshl_add_u64 v[26:27], v[26:27], 2, s[8:9]
	global_load_dword v28, v[6:7], off
	global_load_dword v29, v[22:23], off
	global_load_dword v30, v[24:25], off
	global_load_dword v31, v[26:27], off
	s_waitcnt vmcnt(0)
	v_add_f32_e32 v2, v2, v28
	v_add_f32_e32 v3, v3, v29
	v_add_f32_e32 v0, v0, v30
	v_add_f32_e32 v1, v1, v31
	global_store_dword v[6:7], v2, off
	global_store_dword v[22:23], v3, off
	global_store_dword v[24:25], v0, off
	global_store_dword v[26:27], v1, off
	s_branch .LBB0_703

.LBB0_1027:
	s_or_b64 exec, exec, s[8:9]
	s_barrier
	s_and_saveexec_b64 s[8:9], s[6:7]
	s_cbranch_execz .LBB0_1014
	v_lshlrev_b32_e32 v5, 9, v16
	v_lshl_or_b32 v4, s0, 4, v17
	v_and_b32_e32 v5, 0x2000, v5
	v_add_u32_e32 v4, v4, v5
	v_readlane_b32 s6, v240, 17
	v_ashrrev_i32_e32 v5, 31, v4
	v_readlane_b32 s7, v240, 18
	s_nop 1
	v_lshl_add_u64 v[6:7], v[4:5], 2, s[6:7]
	v_add_u32_e32 v22, 0x800, v4
	v_ashrrev_i32_e32 v23, 31, v22
	v_lshl_add_u64 v[22:23], v[22:23], 2, s[6:7]
	v_add_u32_e32 v24, 0x1000, v4
	v_ashrrev_i32_e32 v25, 31, v24
	v_lshl_add_u64 v[24:25], v[24:25], 2, s[6:7]
	v_add_u32_e32 v26, 0x1800, v4
	v_ashrrev_i32_e32 v27, 31, v26
	v_lshl_add_u64 v[26:27], v[26:27], 2, s[6:7]
	global_load_dword v28, v[6:7], off
	global_load_dword v29, v[22:23], off
	global_load_dword v30, v[24:25], off
	global_load_dword v31, v[26:27], off
	s_waitcnt vmcnt(0)
	v_add_f32_e32 v2, v2, v28
	v_add_f32_e32 v3, v3, v29
	v_add_f32_e32 v0, v0, v30
	v_add_f32_e32 v1, v1, v31
	global_store_dword v[6:7], v2, off
	global_store_dword v[22:23], v3, off
	global_store_dword v[24:25], v0, off
	global_store_dword v[26:27], v1, off
	s_branch .LBB0_1014

.LBB0_1369:
	s_or_b64 exec, exec, s[8:9]
	s_barrier
	s_and_saveexec_b64 s[8:9], s[6:7]
	s_cbranch_execz .LBB0_1362
	v_lshlrev_b32_e32 v4, 9, v12
	v_and_or_b32 v4, v4, s49, v13
	v_add_u32_e32 v4, s4, v4
	v_readlane_b32 s6, v240, 17
	v_ashrrev_i32_e32 v5, 31, v4
	v_readlane_b32 s7, v240, 18
	s_nop 1
	v_lshl_add_u64 v[6:7], v[4:5], 2, s[6:7]
	v_add_u32_e32 v22, 0x800, v4
	v_ashrrev_i32_e32 v23, 31, v22
	v_lshl_add_u64 v[22:23], v[22:23], 2, s[6:7]
	v_add_u32_e32 v24, 0x1000, v4
	v_ashrrev_i32_e32 v25, 31, v24
	v_lshl_add_u64 v[24:25], v[24:25], 2, s[6:7]
	v_add_u32_e32 v26, 0x1800, v4
	v_ashrrev_i32_e32 v27, 31, v26
	v_lshl_add_u64 v[26:27], v[26:27], 2, s[6:7]
	global_load_dword v28, v[6:7], off
	global_load_dword v29, v[22:23], off
	global_load_dword v30, v[24:25], off
	global_load_dword v31, v[26:27], off
	s_waitcnt vmcnt(0)
	v_add_f32_e32 v2, v2, v28
	v_add_f32_e32 v3, v3, v29
	v_add_f32_e32 v0, v0, v30
	v_add_f32_e32 v1, v1, v31
	global_store_dword v[6:7], v2, off
	global_store_dword v[22:23], v3, off
	global_store_dword v[24:25], v0, off
	global_store_dword v[26:27], v1, off
	s_branch .LBB0_1362

.LBB0_1599:
	s_or_b64 exec, exec, s[6:7]
	s_barrier
	s_and_saveexec_b64 s[6:7], s[4:5]
	s_cbranch_execz .LBB0_1552
	v_lshlrev_b32_e32 v4, 9, v14
	v_and_or_b32 v4, v4, s49, v15
	v_add_u32_e32 v4, s10, v4
	v_readlane_b32 s4, v240, 17
	v_ashrrev_i32_e32 v5, 31, v4
	v_readlane_b32 s5, v240, 18
	s_nop 1
	v_lshl_add_u64 v[6:7], v[4:5], 2, s[4:5]
	v_add_u32_e32 v22, 0x800, v4
	v_ashrrev_i32_e32 v23, 31, v22
	v_lshl_add_u64 v[22:23], v[22:23], 2, s[4:5]
	v_add_u32_e32 v24, 0x1000, v4
	v_ashrrev_i32_e32 v25, 31, v24
	v_lshl_add_u64 v[24:25], v[24:25], 2, s[4:5]
	v_add_u32_e32 v26, 0x1800, v4
	v_ashrrev_i32_e32 v27, 31, v26
	v_lshl_add_u64 v[26:27], v[26:27], 2, s[4:5]
	global_load_dword v28, v[6:7], off
	global_load_dword v29, v[22:23], off
	global_load_dword v30, v[24:25], off
	global_load_dword v31, v[26:27], off
	s_waitcnt vmcnt(0)
	v_add_f32_e32 v2, v2, v28
	v_add_f32_e32 v3, v3, v29
	v_add_f32_e32 v0, v0, v30
	v_add_f32_e32 v1, v1, v31
	global_store_dword v[6:7], v2, off
	global_store_dword v[22:23], v3, off
	global_store_dword v[24:25], v0, off
	global_store_dword v[26:27], v1, off
	s_branch .LBB0_1552
